# GEMM tile-start test shortened: branch on the SCC of s_and_b32 instead of a separate s_cmp
# baseline (speedup 1.0000x reference)
; #define MFMA(a, b, c) __builtin_amdgcn_mfma_f32_32x32x16_bf16((a), (b), (c), 0, 0, 0)
; DI f32x16 zero16() { f32x16 z; for (int i = 0; i < 16; ++i) z[i] = 0.f; return z; }
;     ...
;   const int drr = lane >> 3, dch = (lane & 7) ^ (((w & 1) * 4 + (drr >> 1)) & 7);
;   const int drow = w * 8 + drr, dcol = dch * 8;
;   const unsigned dA = (unsigned)(drow * lda + dcol), dB = (unsigned)(drow * K + dcol);
;     ...
;   const int fP = r * 128, fsw = (r >> 1) & 7;
;   const int fA = wm * 8192 + fP, fB = 32768 + wn * 16384 + fP;
;   f32x16 acc[2][4];
; #pragma unroll
;   for (int i = 0; i < 2; ++i)
; #pragma unroll
;     for (int j = 0; j < 4; ++j) acc[i][j] = zero16();
;   __syncthreads();
;   G_DMA(0, 0);
;   asm volatile("s_waitcnt vmcnt(0)" ::: "memory");
;   asm volatile("s_waitcnt lgkmcnt(0)" ::: "memory"); __builtin_amdgcn_s_barrier(); asm volatile("" ::: "memory");
;   int cur = 0;
;   for (int s = 0; s < S; ++s) {
;     G_DMA(s + 1, cur ^ BUFB);
;     {
;       const char* Ab = smem + cur + fA;
;       const char* Bb = smem + cur + fB;
;       __builtin_amdgcn_sched_barrier(0);
; #pragma unroll
;       for (int kk = 0; kk < 4; ++kk) {
;         const int ko = (((kk * 2 + hh) ^ fsw) << 4);
;         bf16x8 af[2], wf[4];
;         af[0] = *(const bf16x8*)(Ab + ko); af[1] = *(const bf16x8*)(Ab + 4096 + ko);
; #pragma unroll
;         for (int ni = 0; ni < 4; ++ni) wf[ni] = *(const bf16x8*)(Bb + ni * 4096 + ko);
; #pragma unroll
;         for (int mi = 0; mi < 2; ++mi)
; #pragma unroll
;           for (int ni = 0; ni < 4; ++ni) acc[mi][ni] = MFMA(wf[ni], af[mi], acc[mi][ni]);
;         if (kk == 1) __builtin_amdgcn_sched_barrier(0);
;       }
.LBB0_218:
	v_add3_u32 v244, s25, v131, v140
	v_add3_u32 v245, s25, v141, v140
	v_add_u32_e32 v187, v245, v144
	v_add_u32_e32 v208, v244, v144
	ds_read_b128 v[188:191], v187 offset:32768
	ds_read_b128 v[204:207], v208
	ds_read_b128 v[192:195], v187 offset:36864
	ds_read_b128 v[196:199], v187 offset:40960
	ds_read_b128 v[200:203], v187 offset:45056
	ds_read_b128 v[216:219], v208 offset:4096
	v_add_u32_e32 v209, v245, v145
	v_add_u32_e32 v215, v244, v145
	ds_read_b128 v[220:223], v209 offset:32768
	ds_read_b128 v[236:239], v215
	ds_read_b128 v[224:227], v209 offset:36864
	ds_read_b128 v[228:231], v209 offset:40960
	ds_read_b128 v[232:235], v209 offset:45056
	ds_read_b128 v[240:243], v215 offset:4096
	s_add_i32 s46, s8, 1
	s_cmp_lt_u32 s46, s58
	s_cselect_b32 s22, s46, s59
	s_lshl_b32 s23, s22, 1
	s_andn2_b32 s23, s23, 31
	s_add_i32 s23, s23, s33
	s_lshr_b32 s23, s23, 3
	s_mov_b32 s9, s25
	s_and_b32 s25, s23, 4
	s_or_b32 s25, s25, s45
	s_and_b32 s23, s23, 0xfffff8
	s_or_b32 s28, s23, s74
	s_lshl_b32 s23, s25, 19
	s_add_u32 s23, s7, s23
	s_addc_u32 s25, s24, 0
	s_lshl_b32 s22, s22, 7
	s_and_b32 s44, s22, 0x780
	s_add_u32 s22, s23, s44
	s_addc_u32 s23, s25, 0
	s_lshl_b32 s40, s28, 8
	s_ashr_i32 s41, s40, 31
	s_lshl_b64 s[40:41], s[40:41], 11
	s_add_u32 s28, s62, s40
	s_addc_u32 s40, s63, s41
	s_xor_b32 s25, s9, 0x10000
	v_add_u32_e32 v128, s25, v142
	v_lshl_add_u64 v[136:137], s[22:23], 0, v[132:133]
	v_readfirstlane_b32 s22, v128
	v_add_u32_e32 v148, 0x2000, v128
	s_mov_b32 m0, s22
	s_mov_b64 s[50:51], 0x20000
	v_readfirstlane_b32 s22, v148
	v_add_u32_e32 v148, 0x4000, v128
	global_load_lds_dwordx4 v[136:137], off
	s_and_b32 s9, s8, 15
	s_cbranch_scc0 .Lgz_2
	s_waitcnt lgkmcnt(10)
	v_mfma_f32_32x32x16_bf16 v[112:127], v[188:191], v[204:207], v[112:127]
	s_waitcnt lgkmcnt(9)
	v_mfma_f32_32x32x16_bf16 v[96:111], v[192:195], v[204:207], v[96:111]
	v_lshl_add_u64 v[138:139], v[136:137], 0, s[50:51]
	s_mov_b32 m0, s22
	s_mov_b64 s[48:49], 0x40000
	v_readfirstlane_b32 s22, v148
	global_load_lds_dwordx4 v[138:139], off
	s_waitcnt lgkmcnt(8)
	v_mfma_f32_32x32x16_bf16 v[80:95], v[196:199], v[204:207], v[80:95]
	s_waitcnt lgkmcnt(7)
	v_mfma_f32_32x32x16_bf16 v[64:79], v[200:203], v[204:207], v[64:79]
	v_lshl_add_u64 v[138:139], v[136:137], 0, s[48:49]
	s_mov_b32 m0, s22
	s_mov_b64 s[52:53], 0x60000
	global_load_lds_dwordx4 v[138:139], off
	s_waitcnt lgkmcnt(6)
	v_mfma_f32_32x32x16_bf16 v[48:63], v[188:191], v[216:219], v[48:63]
	v_mfma_f32_32x32x16_bf16 v[32:47], v[192:195], v[216:219], v[32:47]
	v_add_u32_e32 v138, 0x6000, v128
	v_lshl_add_u64 v[136:137], v[136:137], 0, s[52:53]
	v_readfirstlane_b32 s22, v138
	s_mov_b32 m0, s22
	s_add_u32 s22, s28, s44
	s_addc_u32 s23, s40, 0
	v_add_u32_e32 v138, 0x8000, v128
	global_load_lds_dwordx4 v[136:137], off
	v_mfma_f32_32x32x16_bf16 v[16:31], v[196:199], v[216:219], v[16:31]
	v_mfma_f32_32x32x16_bf16 v[0:15], v[200:203], v[216:219], v[0:15]
	v_lshl_add_u64 v[136:137], s[22:23], 0, v[132:133]
	v_readfirstlane_b32 s22, v138
	v_add_u32_e32 v148, 0xa000, v128
	s_mov_b32 m0, s22
	v_readfirstlane_b32 s22, v148
	v_add_u32_e32 v148, 0xc000, v128
	global_load_lds_dwordx4 v[136:137], off
	s_branch .Lgj_2

; #define MFMA(a, b, c) __builtin_amdgcn_mfma_f32_32x32x16_bf16((a), (b), (c), 0, 0, 0)
; DI f32x16 zero16() { f32x16 z; for (int i = 0; i < 16; ++i) z[i] = 0.f; return z; }
;     ...
;   const int drr = lane >> 3, dch = (lane & 7) ^ (((w & 1) * 4 + (drr >> 1)) & 7);
;   const int drow = w * 8 + drr, dcol = dch * 8;
;   const unsigned dA = (unsigned)(drow * lda + dcol), dB = (unsigned)(drow * K + dcol);
;     ...
;   const int fP = r * 128, fsw = (r >> 1) & 7;
;   const int fA = wm * 8192 + fP, fB = 32768 + wn * 16384 + fP;
;   f32x16 acc[2][4];
; #pragma unroll
;   for (int i = 0; i < 2; ++i)
; #pragma unroll
;     for (int j = 0; j < 4; ++j) acc[i][j] = zero16();
;   __syncthreads();
;   G_DMA(0, 0);
;   asm volatile("s_waitcnt vmcnt(0)" ::: "memory");
;   asm volatile("s_waitcnt lgkmcnt(0)" ::: "memory"); __builtin_amdgcn_s_barrier(); asm volatile("" ::: "memory");
;   int cur = 0;
;   for (int s = 0; s < S; ++s) {
;     G_DMA(s + 1, cur ^ BUFB);
;     {
;       const char* Ab = smem + cur + fA;
;       const char* Bb = smem + cur + fB;
;       __builtin_amdgcn_sched_barrier(0);
; #pragma unroll
;       for (int kk = 0; kk < 4; ++kk) {
;         const int ko = (((kk * 2 + hh) ^ fsw) << 4);
;         bf16x8 af[2], wf[4];
;         af[0] = *(const bf16x8*)(Ab + ko); af[1] = *(const bf16x8*)(Ab + 4096 + ko);
; #pragma unroll
;         for (int ni = 0; ni < 4; ++ni) wf[ni] = *(const bf16x8*)(Bb + ni * 4096 + ko);
; #pragma unroll
;         for (int mi = 0; mi < 2; ++mi)
; #pragma unroll
;           for (int ni = 0; ni < 4; ++ni) acc[mi][ni] = MFMA(wf[ni], af[mi], acc[mi][ni]);
;         if (kk == 1) __builtin_amdgcn_sched_barrier(0);
;       }
.LBB0_741:
	v_add3_u32 v187, s6, v131, v140
	v_add3_u32 v208, s6, v141, v140
	v_add_u32_e32 v182, v208, v144
	v_add_u32_e32 v183, v187, v144
	ds_read_b128 v[192:195], v182 offset:32768
	ds_read_b128 v[216:219], v183
	ds_read_b128 v[196:199], v182 offset:36864
	ds_read_b128 v[200:203], v182 offset:40960
	ds_read_b128 v[204:207], v182 offset:45056
	ds_read_b128 v[220:223], v183 offset:4096
	v_add_u32_e32 v184, v208, v145
	v_add_u32_e32 v185, v187, v145
	ds_read_b128 v[224:227], v184 offset:32768
	ds_read_b128 v[240:243], v185
	ds_read_b128 v[228:231], v184 offset:36864
	ds_read_b128 v[232:235], v184 offset:40960
	ds_read_b128 v[236:239], v184 offset:45056
	ds_read_b128 v[244:247], v185 offset:4096
	s_add_i32 s7, s8, 1
	s_mov_b32 s9, s6
	s_cmp_lt_u32 s7, s22
	v_readlane_b32 s6, v251, 36
	s_cselect_b32 s24, s7, s6
	s_lshl_b32 s6, s24, 1
	s_and_b32 s6, s6, 0x7ffffe0
	s_add_i32 s6, s6, s33
	s_lshl_b32 s6, s6, 5
	s_and_b32 s22, s6, 0xffffff00
	s_ashr_i32 s23, s22, 31
	s_lshl_b64 s[22:23], s[22:23], 11
	s_add_u32 s22, s62, s22
	s_addc_u32 s23, s63, s23
	s_xor_b32 s6, s9, 0x10000
	v_add_u32_e32 v128, s6, v142
	s_lshl_b32 s24, s24, 7
	s_and_b32 s28, s24, 0x780
	v_readfirstlane_b32 s24, v128
	v_add_u32_e32 v152, 0x2000, v128
	v_lshl_add_u64 v[148:149], v[134:135], 0, s[28:29]
	s_mov_b32 m0, s24
	s_mov_b64 s[44:45], 0x20000
	v_readfirstlane_b32 s24, v152
	v_add_u32_e32 v152, 0x4000, v128
	global_load_lds_dwordx4 v[148:149], off
	s_and_b32 s9, s8, 15
	s_cbranch_scc0 .Lgz_5
	s_waitcnt lgkmcnt(10)
	v_mfma_f32_32x32x16_bf16 v[112:127], v[192:195], v[216:219], v[112:127]
	s_waitcnt lgkmcnt(9)
	v_mfma_f32_32x32x16_bf16 v[96:111], v[196:199], v[216:219], v[96:111]
	v_lshl_add_u64 v[150:151], v[148:149], 0, s[44:45]
	s_mov_b32 m0, s24
	s_mov_b64 s[42:43], 0x40000
	v_readfirstlane_b32 s24, v152
	global_load_lds_dwordx4 v[150:151], off
	s_waitcnt lgkmcnt(8)
	v_mfma_f32_32x32x16_bf16 v[80:95], v[200:203], v[216:219], v[80:95]
	s_waitcnt lgkmcnt(7)
	v_mfma_f32_32x32x16_bf16 v[64:79], v[204:207], v[216:219], v[64:79]
	v_lshl_add_u64 v[150:151], v[148:149], 0, s[42:43]
	s_mov_b32 m0, s24
	s_mov_b64 s[46:47], 0x60000
	global_load_lds_dwordx4 v[150:151], off
	s_waitcnt lgkmcnt(6)
	v_mfma_f32_32x32x16_bf16 v[48:63], v[192:195], v[220:223], v[48:63]
	v_mfma_f32_32x32x16_bf16 v[32:47], v[196:199], v[220:223], v[32:47]
	v_add_u32_e32 v150, 0x6000, v128
	s_add_u32 s22, s22, s28
	v_readfirstlane_b32 s24, v150
	v_lshl_add_u64 v[148:149], v[148:149], 0, s[46:47]
	s_mov_b32 m0, s24
	s_addc_u32 s23, s23, 0
	v_add_u32_e32 v150, 0x8000, v128
	global_load_lds_dwordx4 v[148:149], off
	v_mfma_f32_32x32x16_bf16 v[16:31], v[200:203], v[220:223], v[16:31]
	v_mfma_f32_32x32x16_bf16 v[0:15], v[204:207], v[220:223], v[0:15]
	v_lshl_add_u64 v[148:149], s[22:23], 0, v[132:133]
	v_readfirstlane_b32 s22, v150
	v_add_u32_e32 v152, 0xa000, v128
	s_mov_b32 m0, s22
	v_readfirstlane_b32 s22, v152
	v_add_u32_e32 v152, 0xc000, v128
	global_load_lds_dwordx4 v[148:149], off
	s_branch .Lgj_5

; #define MFMA(a, b, c) __builtin_amdgcn_mfma_f32_32x32x16_bf16((a), (b), (c), 0, 0, 0)
; DI f32x16 zero16() { f32x16 z; for (int i = 0; i < 16; ++i) z[i] = 0.f; return z; }
;     ...
;   const int drr = lane >> 3, dch = (lane & 7) ^ (((w & 1) * 4 + (drr >> 1)) & 7);
;   const int drow = w * 8 + drr, dcol = dch * 8;
;   const unsigned dA = (unsigned)(drow * lda + dcol), dB = (unsigned)(drow * K + dcol);
;     ...
;   const int fP = r * 128, fsw = (r >> 1) & 7;
;   const int fA = wm * 8192 + fP, fB = 32768 + wn * 16384 + fP;
;   f32x16 acc[2][4];
; #pragma unroll
;   for (int i = 0; i < 2; ++i)
; #pragma unroll
;     for (int j = 0; j < 4; ++j) acc[i][j] = zero16();
;   __syncthreads();
;   G_DMA(0, 0);
;   asm volatile("s_waitcnt vmcnt(0)" ::: "memory");
;   asm volatile("s_waitcnt lgkmcnt(0)" ::: "memory"); __builtin_amdgcn_s_barrier(); asm volatile("" ::: "memory");
;   int cur = 0;
;   for (int s = 0; s < S; ++s) {
;     G_DMA(s + 1, cur ^ BUFB);
;     {
;       const char* Ab = smem + cur + fA;
;       const char* Bb = smem + cur + fB;
;       __builtin_amdgcn_sched_barrier(0);
; #pragma unroll
;       for (int kk = 0; kk < 4; ++kk) {
;         const int ko = (((kk * 2 + hh) ^ fsw) << 4);
;         bf16x8 af[2], wf[4];
;         af[0] = *(const bf16x8*)(Ab + ko); af[1] = *(const bf16x8*)(Ab + 4096 + ko);
; #pragma unroll
;         for (int ni = 0; ni < 4; ++ni) wf[ni] = *(const bf16x8*)(Bb + ni * 4096 + ko);
; #pragma unroll
;         for (int mi = 0; mi < 2; ++mi)
; #pragma unroll
;           for (int ni = 0; ni < 4; ++ni) acc[mi][ni] = MFMA(wf[ni], af[mi], acc[mi][ni]);
;         if (kk == 1) __builtin_amdgcn_sched_barrier(0);
;       }
.LBB0_1108:
	v_add3_u32 v215, s6, v187, v189
	v_add3_u32 v244, s6, v188, v189
	v_add_u32_e32 v182, v244, v190
	v_add_u32_e32 v183, v215, v190
	ds_read_b128 v[170:173], v182 offset:32768
	ds_read_b128 v[194:197], v183
	ds_read_b128 v[198:201], v182 offset:36864
	ds_read_b128 v[202:205], v182 offset:40960
	ds_read_b128 v[206:209], v182 offset:45056
	ds_read_b128 v[216:219], v183 offset:4096
	v_add_u32_e32 v184, v244, v191
	v_add_u32_e32 v185, v215, v191
	ds_read_b128 v[220:223], v184 offset:32768
	ds_read_b128 v[236:239], v185
	ds_read_b128 v[224:227], v184 offset:36864
	ds_read_b128 v[228:231], v184 offset:40960
	ds_read_b128 v[232:235], v184 offset:45056
	ds_read_b128 v[240:243], v185 offset:4096
	s_add_i32 s7, s8, 1
	s_mov_b32 s9, s6
	s_cmp_lt_u32 s7, s60
	v_readlane_b32 s6, v253, 59
	s_cselect_b32 s6, s7, s6
	s_lshl_b32 s22, s6, 1
	s_andn2_b32 s22, s22, 31
	s_add_i32 s22, s22, s33
	s_lshr_b32 s23, s22, 4
	s_lshr_b32 s22, s22, 3
	s_and_b32 s22, s22, 12
	v_readlane_b32 s46, v252, 41
	s_and_b32 s23, s23, 0xfffff8
	s_or_b32 s22, s22, s46
	s_or_b32 s24, s23, s74
	s_lshl_b32 s22, s22, 19
	v_readlane_b32 s40, v253, 39
	v_readlane_b32 s41, v253, 40
	s_add_u32 s22, s40, s22
	s_addc_u32 s23, s41, 0
	s_lshl_b32 s6, s6, 7
	s_and_b32 s28, s6, 0x780
	s_add_u32 s22, s22, s28
	s_addc_u32 s23, s23, 0
	s_lshl_b32 s24, s24, 8
	s_ashr_i32 s25, s24, 31
	s_lshl_b64 s[24:25], s[24:25], 11
	s_add_u32 s24, s62, s24
	s_addc_u32 s25, s63, s25
	s_xor_b32 s6, s9, 0x10000
	v_add_u32_e32 v245, s6, v131
	v_lshl_add_u64 v[246:247], s[22:23], 0, v[132:133]
	v_readfirstlane_b32 s22, v245
	v_add_u32_e32 v250, 0x2000, v245
	s_mov_b32 m0, s22
	s_mov_b64 s[42:43], 0x20000
	v_readfirstlane_b32 s22, v250
	v_add_u32_e32 v250, 0x4000, v245
	global_load_lds_dwordx4 v[246:247], off
	s_and_b32 s9, s8, 15
	s_cbranch_scc0 .Lgz_6
	s_waitcnt lgkmcnt(10)
	v_mfma_f32_32x32x16_bf16 v[112:127], v[170:173], v[194:197], v[112:127]
	s_waitcnt lgkmcnt(9)
	v_mfma_f32_32x32x16_bf16 v[96:111], v[198:201], v[194:197], v[96:111]
	v_lshl_add_u64 v[248:249], v[246:247], 0, s[42:43]
	s_mov_b32 m0, s22
	s_mov_b64 s[40:41], 0x40000
	v_readfirstlane_b32 s22, v250
	v_add_u32_e32 v250, 0x6000, v245
	global_load_lds_dwordx4 v[248:249], off
	s_waitcnt lgkmcnt(8)
	v_mfma_f32_32x32x16_bf16 v[80:95], v[202:205], v[194:197], v[80:95]
	s_waitcnt lgkmcnt(7)
	v_mfma_f32_32x32x16_bf16 v[64:79], v[206:209], v[194:197], v[64:79]
	v_lshl_add_u64 v[248:249], v[246:247], 0, s[40:41]
	s_mov_b32 m0, s22
	v_readfirstlane_b32 s22, v250
	global_load_lds_dwordx4 v[248:249], off
	s_waitcnt lgkmcnt(6)
	v_mfma_f32_32x32x16_bf16 v[48:63], v[170:173], v[216:219], v[48:63]
	v_mfma_f32_32x32x16_bf16 v[32:47], v[198:201], v[216:219], v[32:47]
	s_mov_b64 s[44:45], 0x60000
	s_mov_b32 m0, s22
	s_add_u32 s22, s24, s28
	v_lshl_add_u64 v[246:247], v[246:247], 0, s[44:45]
	s_addc_u32 s23, s25, 0
	v_add_u32_e32 v250, 0x8000, v245
	global_load_lds_dwordx4 v[246:247], off
	v_mfma_f32_32x32x16_bf16 v[16:31], v[202:205], v[216:219], v[16:31]
	v_mfma_f32_32x32x16_bf16 v[0:15], v[206:209], v[216:219], v[0:15]
	v_lshl_add_u64 v[246:247], s[22:23], 0, v[132:133]
	v_readfirstlane_b32 s22, v250
	v_add_u32_e32 v250, 0xa000, v245
	s_mov_b32 m0, s22
	v_readfirstlane_b32 s22, v250
	v_add_u32_e32 v250, 0xc000, v245
	global_load_lds_dwordx4 v[246:247], off
	s_branch .Lgj_6

; #define MFMA(a, b, c) __builtin_amdgcn_mfma_f32_32x32x16_bf16((a), (b), (c), 0, 0, 0)
; DI f32x16 zero16() { f32x16 z; for (int i = 0; i < 16; ++i) z[i] = 0.f; return z; }
;     ...
;   const int drr = lane >> 3, dch = (lane & 7) ^ (((w & 1) * 4 + (drr >> 1)) & 7);
;   const int drow = w * 8 + drr, dcol = dch * 8;
;   const unsigned dA = (unsigned)(drow * lda + dcol), dB = (unsigned)(drow * K + dcol);
;     ...
;   const int fP = r * 128, fsw = (r >> 1) & 7;
;   const int fA = wm * 8192 + fP, fB = 32768 + wn * 16384 + fP;
;   f32x16 acc[2][4];
; #pragma unroll
;   for (int i = 0; i < 2; ++i)
; #pragma unroll
;     for (int j = 0; j < 4; ++j) acc[i][j] = zero16();
;   __syncthreads();
;   G_DMA(0, 0);
;   asm volatile("s_waitcnt vmcnt(0)" ::: "memory");
;   asm volatile("s_waitcnt lgkmcnt(0)" ::: "memory"); __builtin_amdgcn_s_barrier(); asm volatile("" ::: "memory");
;   int cur = 0;
;   for (int s = 0; s < S; ++s) {
;     G_DMA(s + 1, cur ^ BUFB);
;     {
;       const char* Ab = smem + cur + fA;
;       const char* Bb = smem + cur + fB;
;       __builtin_amdgcn_sched_barrier(0);
; #pragma unroll
;       for (int kk = 0; kk < 4; ++kk) {
;         const int ko = (((kk * 2 + hh) ^ fsw) << 4);
;         bf16x8 af[2], wf[4];
;         af[0] = *(const bf16x8*)(Ab + ko); af[1] = *(const bf16x8*)(Ab + 4096 + ko);
; #pragma unroll
;         for (int ni = 0; ni < 4; ++ni) wf[ni] = *(const bf16x8*)(Bb + ni * 4096 + ko);
; #pragma unroll
;         for (int mi = 0; mi < 2; ++mi)
; #pragma unroll
;           for (int ni = 0; ni < 4; ++ni) acc[mi][ni] = MFMA(wf[ni], af[mi], acc[mi][ni]);
;         if (kk == 1) __builtin_amdgcn_sched_barrier(0);
;       }
.LBB0_1293:
	v_add3_u32 v187, s23, v131, v138
	v_add3_u32 v208, s23, v139, v138
	v_add_u32_e32 v182, v208, v142
	v_add_u32_e32 v183, v187, v142
	ds_read_b128 v[192:195], v182 offset:32768
	ds_read_b128 v[216:219], v183
	ds_read_b128 v[196:199], v182 offset:36864
	ds_read_b128 v[200:203], v182 offset:40960
	ds_read_b128 v[204:207], v182 offset:45056
	ds_read_b128 v[220:223], v183 offset:4096
	v_add_u32_e32 v184, v208, v143
	v_add_u32_e32 v185, v187, v143
	ds_read_b128 v[224:227], v184 offset:32768
	ds_read_b128 v[240:243], v185
	ds_read_b128 v[228:231], v184 offset:36864
	ds_read_b128 v[232:235], v184 offset:40960
	ds_read_b128 v[236:239], v184 offset:45056
	ds_read_b128 v[244:247], v185 offset:4096
	s_add_i32 s44, s8, 1
	s_mov_b32 s9, s23
	s_cmp_lt_u32 s44, s46
	v_readlane_b32 s23, v252, 57
	s_cselect_b32 s23, s44, s23
	s_lshl_b32 s24, s23, 1
	s_andn2_b32 s24, s24, 31
	s_add_i32 s24, s24, s33
	s_lshr_b32 s24, s24, 3
	s_and_b32 s25, s24, 4
	s_or_b32 s25, s25, s47
	s_and_b32 s24, s24, 0xfffff8
	s_or_b32 s28, s24, s74
	s_lshl_b32 s24, s25, 19
	s_add_u32 s24, s7, s24
	s_addc_u32 s25, s22, 0
	s_lshl_b32 s23, s23, 7
	s_and_b32 s45, s23, 0x780
	s_add_u32 s24, s24, s45
	s_addc_u32 s25, s25, 0
	s_lshl_b32 s40, s28, 8
	s_ashr_i32 s41, s40, 31
	s_lshl_b64 s[40:41], s[40:41], 11
	s_add_u32 s28, s72, s40
	s_addc_u32 s40, s73, s41
	s_xor_b32 s23, s9, 0x10000
	v_add_u32_e32 v128, s23, v140
	v_lshl_add_u64 v[136:137], s[24:25], 0, v[132:133]
	v_readfirstlane_b32 s24, v128
	v_add_u32_e32 v148, 0x2000, v128
	s_mov_b32 m0, s24
	s_mov_b64 s[48:49], 0x20000
	v_readfirstlane_b32 s24, v148
	v_add_u32_e32 v148, 0x4000, v128
	global_load_lds_dwordx4 v[136:137], off
	s_add_i32 s9, s9, 0
	s_and_b32 s9, s8, 15
	s_cbranch_scc0 .Lgz_9
	s_waitcnt lgkmcnt(10)
	v_mfma_f32_32x32x16_bf16 v[112:127], v[192:195], v[216:219], v[112:127]
	s_waitcnt lgkmcnt(9)
	v_mfma_f32_32x32x16_bf16 v[96:111], v[196:199], v[216:219], v[96:111]
	v_lshl_add_u64 v[146:147], v[136:137], 0, s[48:49]
	s_mov_b32 m0, s24
	s_mov_b64 s[50:51], 0x40000
	v_readfirstlane_b32 s24, v148
	global_load_lds_dwordx4 v[146:147], off
	s_waitcnt lgkmcnt(8)
	v_mfma_f32_32x32x16_bf16 v[80:95], v[200:203], v[216:219], v[80:95]
	s_waitcnt lgkmcnt(7)
	v_mfma_f32_32x32x16_bf16 v[64:79], v[204:207], v[216:219], v[64:79]
	v_lshl_add_u64 v[146:147], v[136:137], 0, s[50:51]
	s_mov_b32 m0, s24
	s_mov_b64 s[52:53], 0x60000
	global_load_lds_dwordx4 v[146:147], off
	s_waitcnt lgkmcnt(6)
	v_mfma_f32_32x32x16_bf16 v[48:63], v[192:195], v[220:223], v[48:63]
	v_mfma_f32_32x32x16_bf16 v[32:47], v[196:199], v[220:223], v[32:47]
	v_add_u32_e32 v146, 0x6000, v128
	v_lshl_add_u64 v[136:137], v[136:137], 0, s[52:53]
	v_readfirstlane_b32 s24, v146
	s_mov_b32 m0, s24
	s_add_u32 s24, s28, s45
	s_addc_u32 s25, s40, 0
	v_add_u32_e32 v146, 0x8000, v128
	global_load_lds_dwordx4 v[136:137], off
	v_mfma_f32_32x32x16_bf16 v[16:31], v[200:203], v[220:223], v[16:31]
	v_mfma_f32_32x32x16_bf16 v[0:15], v[204:207], v[220:223], v[0:15]
	v_lshl_add_u64 v[136:137], s[24:25], 0, v[132:133]
	v_readfirstlane_b32 s24, v146
	v_add_u32_e32 v148, 0xa000, v128
	s_mov_b32 m0, s24
	v_readfirstlane_b32 s24, v148
	v_add_u32_e32 v148, 0xc000, v128
	global_load_lds_dwordx4 v[136:137], off
	s_branch .Lgj_9
